# v18 with hardened placement guard (grid must be 256, verdict lane initialised at entry); same barrier scheme
# speedup vs baseline: 1.0337x; 1.0030x over previous
; #define LAS __attribute__((address_space(3)))
; #define OPAQUE_TID() int tid = MYTID(); asm volatile("" : "+v"(tid)); const int lane = tid & 63, wave = __builtin_amdgcn_readfirstlane(tid >> 6); (void)lane; (void)wave
; __global__ void __launch_bounds__(NTHREADS, 2) fwd_kernel(Args a) {
;     ...
;     const int lo = a.ph_lo, hi = a.ph_hi;
;     const int wave_s = __builtin_amdgcn_readfirstlane(threadIdx.x >> 6);
;     ...
;     { volatile LAS unsigned* stw = (volatile LAS unsigned*)(lds + 131072); if (threadIdx.x == 0) { stw[0] = 0u; stw[1] = 0u; } __syncthreads(); }
;     (void)xcd_barrier_post((unsigned*)ws, (volatile LAS unsigned*)(lds + 131072), (int)threadIdx.x);
;     if (IN(0)) { OPAQUE_TID(); prep_phase(a, lds, vcu, G, wave, lane); }
.LBB0_7:
	s_or_b64 exec, exec, s[2:3]
	s_andn2_b32 s0, s0, 63
	s_cmp_lt_i32 s42, 1
	v_writelane_b32 v248, s0, 0
	v_writelane_b32 v248, 0, 32
	s_cselect_b64 s[0:1], -1, 0
	s_cmp_gt_i32 s43, 0
	s_cselect_b64 s[2:3], -1, 0
	s_and_b64 s[34:35], s[0:1], s[2:3]
	s_andn2_b64 vcc, exec, s[34:35]
	v_mbcnt_lo_u32_b32 v230, -1, 0
	s_cbranch_vccnz .LBB0_312

; __device__ __forceinline__ unsigned xb_ld(unsigned* p)              { return __hip_atomic_load(p, __ATOMIC_RELAXED, __HIP_MEMORY_SCOPE_AGENT); }
; __device__ __forceinline__ unsigned xb_add(unsigned* p, unsigned v) { return __hip_atomic_fetch_add(p, v, __ATOMIC_RELAXED, __HIP_MEMORY_SCOPE_AGENT); }
; __device__ __forceinline__ void xcd_barrier_complete(unsigned* bar, unsigned x, unsigned& nloc, unsigned& nx) {
;     const unsigned G = gridDim.x;
;     unsigned sum, cnt, mine, sp = 0u;
;     for (;;) {
;         sum = 0u; cnt = 0u; mine = 0u;
; #pragma unroll
;         for (unsigned j = 0; j < 16; ++j) { const unsigned c = xb_ld(&bar[XB_XCNT(j)]); sum += c; cnt += (c > 0u) ? 1u : 0u; mine = (j == x) ? c : mine; }
;         if (sum == G) break;
;         __builtin_amdgcn_s_sleep(1);
;         if ((++sp & 255u) == 0u) { if (xb_ld(&bar[XB_TMO])) break; if (sp > XB_SPIN_CAP) { atomicAdd(&bar[XB_TMO], 1u); break; } }
;     }
;     nloc = mine > 0u ? mine : 1u; nx = cnt > 0u ? cnt : 1u;
; }
; __device__ __forceinline__ void xcd_barrier(const XcdBarrier& b, int tid) {
;     asm volatile("s_waitcnt vmcnt(0)" ::: "memory");
;     __syncthreads();
;     if (tid == 0) {
;         unsigned* bar = b.bar;
;         __builtin_amdgcn_s_waitcnt(0);
;         unsigned nloc = b.st[0], nx = b.st[1];
;         if (nloc == 0u) { xcd_barrier_complete(bar, b.x, nloc, nx); b.st[0] = nloc; b.st[1] = nx; }
;         const unsigned old = xb_add(&bar[XB_XSUB(b.x)], 1u);
;         const unsigned gen = old / nloc;
;         if (old + 1u == (gen + 1u) * nloc) {
;             __builtin_amdgcn_fence(__ATOMIC_RELEASE, "agent");
;             asm volatile("s_waitcnt vmcnt(0)" ::: "memory");
;             const unsigned og = xb_add(&bar[XB_TOP], 1u);
;             const unsigned tg = og / nx;
;             if (og + 1u == (tg + 1u) * nx) xb_add(&bar[XB_TOPGEN], 1u);
;             else XB_SPIN(xb_ld(&bar[XB_TOPGEN]) == tg, bar);
;             __builtin_amdgcn_fence(__ATOMIC_ACQUIRE, "agent");
;             xb_add(&bar[XB_XGEN(b.x)], 1u);
;             asm volatile("s_waitcnt vmcnt(0)" ::: "memory");
;         } else {
;             XB_SPIN(xb_ld(&bar[XB_XGEN(b.x)]) == gen, bar);
.LBB0_331:
	s_or_b64 exec, exec, s[10:11]
	v_mov_b32_e32 v14, 0
	global_load_dword v6, v14, s[40:41] offset:1028 sc1
	global_load_dword v7, v14, s[40:41] offset:1284 sc1
	global_load_dword v8, v14, s[40:41] offset:1540 sc1
	global_load_dword v9, v14, s[40:41] offset:1796 sc1
	global_load_dword v10, v14, s[40:41] offset:2052 sc1
	global_load_dword v11, v14, s[40:41] offset:2308 sc1
	global_load_dword v12, v14, s[40:41] offset:2564 sc1
	global_load_dword v13, v14, s[40:41] offset:2820 sc1
	v_cvt_f32_u32_e32 v4, v2
	s_waitcnt vmcnt(0)
	v_readfirstlane_b32 s0, v3
	s_mov_b32 s12, 1
	s_nop 0
	s_cmp_eq_u32 s66, 0x100
	s_cselect_b32 s12, s12, 0
	v_readfirstlane_b32 s1, v6
	s_bcnt1_i32_b32 s1, s1
	s_cmp_eq_u32 s1, 1
	s_cselect_b32 s12, s12, 0
	v_readfirstlane_b32 s1, v7
	s_bcnt1_i32_b32 s1, s1
	s_cmp_eq_u32 s1, 1
	s_cselect_b32 s12, s12, 0
	v_readfirstlane_b32 s1, v8
	s_bcnt1_i32_b32 s1, s1
	s_cmp_eq_u32 s1, 1
	s_cselect_b32 s12, s12, 0
	v_readfirstlane_b32 s1, v9
	s_bcnt1_i32_b32 s1, s1
	s_cmp_eq_u32 s1, 1
	s_cselect_b32 s12, s12, 0
	v_readfirstlane_b32 s1, v10
	s_bcnt1_i32_b32 s1, s1
	s_cmp_eq_u32 s1, 1
	s_cselect_b32 s12, s12, 0
	v_readfirstlane_b32 s1, v11
	s_bcnt1_i32_b32 s1, s1
	s_cmp_eq_u32 s1, 1
	s_cselect_b32 s12, s12, 0
	v_readfirstlane_b32 s1, v12
	s_bcnt1_i32_b32 s1, s1
	s_cmp_eq_u32 s1, 1
	s_cselect_b32 s12, s12, 0
	v_readfirstlane_b32 s1, v13
	s_bcnt1_i32_b32 s1, s1
	s_cmp_eq_u32 s1, 1
	s_cselect_b32 s12, s12, 0
	v_writelane_b32 v248, s12, 32
	v_sub_u32_e32 v3, 0, v2
	v_rcp_iflag_f32_e32 v4, v4
	v_add_u32_e32 v5, s0, v1
	v_mul_f32_e32 v4, 0x4f7ffffe, v4
	v_cvt_u32_f32_e32 v4, v4
	v_mul_lo_u32 v1, v3, v4
	v_mul_hi_u32 v1, v4, v1
	v_add_u32_e32 v1, v4, v1
	v_mul_hi_u32 v1, v5, v1
	v_mul_lo_u32 v3, v1, v2
	v_sub_u32_e32 v3, v5, v3
	v_add_u32_e32 v4, 1, v1
	v_cmp_ge_u32_e32 vcc, v3, v2
	s_nop 1
	v_cndmask_b32_e32 v1, v1, v4, vcc
	v_sub_u32_e32 v4, v3, v2
	v_cndmask_b32_e32 v3, v3, v4, vcc
	v_add_u32_e32 v4, 1, v1
	v_cmp_ge_u32_e32 vcc, v3, v2
	v_add_u32_e32 v3, 1, v5
	s_nop 0
	v_cndmask_b32_e32 v1, v1, v4, vcc
	v_mul_lo_u32 v4, v2, v1
	v_add_u32_e32 v2, v4, v2
	v_cmp_ne_u32_e32 vcc, v3, v2
	s_and_saveexec_b64 s[0:1], vcc
	s_xor_b64 s[8:9], exec, s[0:1]
	s_cbranch_execz .LBB0_345
	s_waitcnt lgkmcnt(0)
	v_mov_b32_e32 v0, 0x2000
	global_load_dword v0, v0, s[6:7] offset:1024 sc1
	s_add_u32 s12, s6, 0x2400
	s_addc_u32 s13, s7, 0
	s_waitcnt vmcnt(0)
	v_cmp_eq_u32_e32 vcc, v0, v1
	s_and_saveexec_b64 s[10:11], vcc
	s_cbranch_execz .LBB0_344
	s_mov_b32 s0, 1
	s_mov_b64 s[14:15], 0
	v_mov_b32_e32 v0, 0
	s_branch .LBB0_335
